# P10 per-head RMSNorm partial-sum reduction (once per unit, before a barrier) moved from two ds_bpermute round trips to v_permlane16/32_swap
# speedup vs baseline: 1.0058x; 1.0016x over previous
.LBB0_991:
	s_or_b64 exec, exec, s[0:1]
	s_waitcnt vmcnt(19)
	v_mfma_f32_16x16x32_bf16 v[8:11], v[8:11], v[76:79], v[84:87]
	s_waitcnt vmcnt(18)
	v_mfma_f32_16x16x32_bf16 v[8:11], v[12:15], v[72:75], v[8:11]
	s_waitcnt vmcnt(17) lgkmcnt(1)
	v_mfma_f32_16x16x32_bf16 v[8:11], v[16:19], v[68:71], v[8:11]
	s_waitcnt vmcnt(16) lgkmcnt(0)
	v_mfma_f32_16x16x32_bf16 v[16:19], v[20:23], v[64:67], v[8:11]
	s_waitcnt vmcnt(15)
	v_mfma_f32_16x16x32_bf16 v[8:11], v[32:35], v[76:79], v[88:91]
	s_waitcnt vmcnt(14)
	v_mfma_f32_16x16x32_bf16 v[8:11], v[36:39], v[72:75], v[8:11]
	s_nop 3
	v_mul_f32_e32 v32, v17, v17
	v_fmac_f32_e32 v32, v16, v16
	v_fmac_f32_e32 v32, v18, v18
	s_waitcnt vmcnt(13)
	v_mfma_f32_16x16x32_bf16 v[8:11], v[40:43], v[68:71], v[8:11]
	v_fmac_f32_e32 v32, v19, v19
	s_waitcnt vmcnt(12)
	v_mfma_f32_16x16x32_bf16 v[12:15], v[44:47], v[64:67], v[8:11]
	s_waitcnt vmcnt(11)
	v_mfma_f32_16x16x32_bf16 v[8:11], v[48:51], v[76:79], v[92:95]
	s_waitcnt vmcnt(10)
	v_mfma_f32_16x16x32_bf16 v[8:11], v[52:55], v[72:75], v[8:11]
	s_nop 3
	v_fmac_f32_e32 v32, v12, v12
	v_fmac_f32_e32 v32, v13, v13
	v_fmac_f32_e32 v32, v14, v14
	s_waitcnt vmcnt(7)
	v_mfma_f32_16x16x32_bf16 v[20:23], v[28:31], v[76:79], v[80:83]
	v_fmac_f32_e32 v32, v15, v15
	v_mfma_f32_16x16x32_bf16 v[8:11], v[56:59], v[68:71], v[8:11]
	s_waitcnt vmcnt(6)
	v_mfma_f32_16x16x32_bf16 v[20:23], v[24:27], v[72:75], v[20:23]
	v_mfma_f32_16x16x32_bf16 v[8:11], v[60:63], v[64:67], v[8:11]
	s_waitcnt vmcnt(5)
	v_mfma_f32_16x16x32_bf16 v[4:7], v[4:7], v[68:71], v[20:23]
	s_waitcnt vmcnt(4)
	v_mfma_f32_16x16x32_bf16 v[0:3], v[0:3], v[64:67], v[4:7]
	s_nop 3
	v_fmac_f32_e32 v32, v8, v8
	v_fmac_f32_e32 v32, v9, v9
	v_fmac_f32_e32 v32, v10, v10
	v_fmac_f32_e32 v32, v11, v11
	v_fmac_f32_e32 v32, v0, v0
	v_fmac_f32_e32 v32, v1, v1
	v_fmac_f32_e32 v32, v2, v2
	v_fmac_f32_e32 v32, v3, v3
	v_mov_b32_e32 v4, v32
	v_mov_b32_e32 v249, v32
	s_nop 1
	v_permlane16_swap_b32_e32 v4, v249
	s_waitcnt lgkmcnt(0)
	v_add_f32_e32 v4, v4, v249
	v_mov_b32_e32 v5, v4
	v_mov_b32_e32 v249, v4
	s_nop 1
	v_permlane32_swap_b32_e32 v5, v249
	s_and_saveexec_b64 s[0:1], s[12:13]
	s_cbranch_execz .LBB0_978
	s_waitcnt lgkmcnt(0)
	v_add_f32_e32 v4, v5, v249
	ds_write_b32 v141, v4 offset:57344
	s_branch .LBB0_978
